# fc1 with the differential-attention interior loop head aligned to 128 bytes instead of 64 (later code shifts by 64 B)
# baseline (speedup 1.0000x reference)
.Ldattn_rare:
	ds_read_b64_tr_b16 v[100:101], v177 offset:33792
	ds_read_b64_tr_b16 v[102:103], v177 offset:34304
	ds_read_b64_tr_b16 v[162:163], v177 offset:33280
	v_max_f32_e32 v0, v0, v0
	v_max_f32_e32 v2, 0, v0
	v_exp_f32_e64 v0, -v2
	v_add_f32_e32 v175, v175, v2
	v_sub_f32_e32 v99, v99, v2
	v_sub_f32_e32 v98, v98, v2
	s_waitcnt lgkmcnt(7)
	v_mfma_f32_32x32x16_bf16 v[36:51], v[156:159], v[144:147], v[36:51]
	v_sub_f32_e32 v97, v97, v2
	v_sub_f32_e32 v96, v96, v2
	v_sub_f32_e32 v95, v95, v2
	v_sub_f32_e32 v94, v94, v2
	v_sub_f32_e32 v93, v93, v2
	v_sub_f32_e32 v92, v92, v2
	v_sub_f32_e32 v91, v91, v2
	s_waitcnt lgkmcnt(5)
	v_mfma_f32_32x32x16_bf16 v[20:35], v[152:155], v[144:147], v[20:35]
	v_sub_f32_e32 v90, v90, v2
	v_sub_f32_e32 v89, v89, v2
	v_sub_f32_e32 v88, v88, v2
	v_sub_f32_e32 v87, v87, v2
	v_sub_f32_e32 v86, v86, v2
	v_sub_f32_e32 v85, v85, v2
	v_sub_f32_e32 v84, v84, v2
	s_waitcnt lgkmcnt(1)
	v_mfma_f32_32x32x16_bf16 v[52:67], v[100:103], v[140:143], v[52:67]
	ds_read_b64_tr_b16 v[100:101], v177 offset:37888
	ds_read_b64_tr_b16 v[102:103], v177 offset:38400
	ds_read_b64_tr_b16 v[158:159], v177 offset:37376
	v_sub_f32_e32 v83, v83, v2
	v_sub_f32_e32 v82, v82, v2
	v_sub_f32_e32 v81, v81, v2
	v_sub_f32_e32 v80, v80, v2
	v_sub_f32_e32 v79, v79, v2
	v_sub_f32_e32 v78, v78, v2
	v_mfma_f32_32x32x16_bf16 v[4:19], v[148:151], v[144:147], v[4:19]
	v_sub_f32_e32 v77, v77, v2
	v_sub_f32_e32 v76, v76, v2
	v_sub_f32_e32 v75, v75, v2
	v_sub_f32_e32 v74, v74, v2
	v_sub_f32_e32 v73, v73, v2
	v_sub_f32_e32 v72, v72, v2
	v_sub_f32_e32 v71, v71, v2
	s_waitcnt lgkmcnt(1)
	v_mfma_f32_32x32x16_bf16 v[36:51], v[100:103], v[140:143], v[36:51]
	ds_read_b64_tr_b16 v[100:101], v177 offset:41984
	ds_read_b64_tr_b16 v[102:103], v177 offset:42496
	ds_read_b64_tr_b16 v[154:155], v177 offset:41472
	v_sub_f32_e32 v70, v70, v2
	v_sub_f32_e32 v69, v69, v2
	v_sub_f32_e32 v68, v68, v2
	v_mov_b32_e32 v2, v1
	v_mov_b32_e32 v3, v1
	v_mul_f32_e32 v173, v173, v0
	s_waitcnt lgkmcnt(1)
	v_mfma_f32_32x32x16_bf16 v[20:35], v[100:103], v[140:143], v[20:35]
	ds_read_b64_tr_b16 v[100:101], v177 offset:46080
	ds_read_b64_tr_b16 v[102:103], v177 offset:46592
	ds_read_b64_tr_b16 v[150:151], v177 offset:45568
	s_waitcnt lgkmcnt(1)
	v_mfma_f32_32x32x16_bf16 v[4:19], v[100:103], v[140:143], v[4:19]
	ds_read_b64_tr_b16 v[100:101], v177 offset:34816
	ds_read_b64_tr_b16 v[102:103], v177 offset:35328
	ds_read_b64_tr_b16 v[104:105], v177 offset:35840
	ds_read_b64_tr_b16 v[106:107], v177 offset:36352
	s_waitcnt lgkmcnt(2)
	v_mfma_f32_32x32x16_bf16 v[52:67], v[100:103], v[136:139], v[52:67]
	ds_read_b64_tr_b16 v[100:101], v177 offset:38912
	ds_read_b64_tr_b16 v[102:103], v177 offset:39424
	ds_read_b64_tr_b16 v[108:109], v177 offset:39936
	ds_read_b64_tr_b16 v[110:111], v177 offset:40448
	s_waitcnt lgkmcnt(2)
	v_mfma_f32_32x32x16_bf16 v[36:51], v[100:103], v[136:139], v[36:51]
	ds_read_b64_tr_b16 v[100:101], v177 offset:43008
	ds_read_b64_tr_b16 v[102:103], v177 offset:43520
	ds_read_b64_tr_b16 v[112:113], v177 offset:44032
	ds_read_b64_tr_b16 v[114:115], v177 offset:44544
	ds_read_b64_tr_b16 v[160:161], v177 offset:32768
	ds_read_b64_tr_b16 v[156:157], v177 offset:36864
	ds_read_b64_tr_b16 v[152:153], v177 offset:40960
	ds_read_b64_tr_b16 v[148:149], v177 offset:45056
	s_waitcnt lgkmcnt(6)
	v_mfma_f32_32x32x16_bf16 v[20:35], v[100:103], v[136:139], v[20:35]
	v_mfma_f32_32x32x16_bf16 v[52:67], v[104:107], v[132:135], v[52:67]
	ds_read_b64_tr_b16 v[100:101], v177 offset:47104
	ds_read_b64_tr_b16 v[102:103], v177 offset:47616
	ds_read_b64_tr_b16 v[104:105], v177 offset:48128
	ds_read_b64_tr_b16 v[106:107], v177 offset:48640
	s_waitcnt lgkmcnt(2)
	v_mfma_f32_32x32x16_bf16 v[4:19], v[100:103], v[136:139], v[4:19]
	s_nop 5
	v_mul_f32_e64 v66, v0, v66
	v_mul_f32_e64 v67, v0, v67
	v_mul_f32_e64 v64, v0, v64
	v_mul_f32_e64 v65, v0, v65
	v_mul_f32_e64 v62, v0, v62
	v_mul_f32_e64 v63, v0, v63
	v_pk_mul_f32 v[60:61], v[0:1], v[60:61] op_sel_hi:[0,1]
	v_pk_mul_f32 v[58:59], v[0:1], v[58:59] op_sel_hi:[0,1]
	v_pk_mul_f32 v[56:57], v[0:1], v[56:57] op_sel_hi:[0,1]
	v_pk_mul_f32 v[54:55], v[0:1], v[54:55] op_sel_hi:[0,1]
	v_mfma_f32_32x32x16_bf16 v[36:51], v[108:111], v[132:135], v[36:51]
	v_mul_f32_e64 v52, v0, v52
	v_mul_f32_e64 v53, v0, v53
	v_xor_b32_e32 v100, 0x80000000, v175
	v_mov_b32_e32 v101, v100
	v_mov_b32_e32 v102, v100
	v_mov_b32_e32 v103, v100
	v_mov_b32_e32 v108, v100
	v_mov_b32_e32 v109, v100
	v_mfma_f32_32x32x16_bf16 v[20:35], v[112:115], v[132:135], v[20:35]
	s_nop 2
	v_mul_f32_e64 v50, v0, v50
	v_mul_f32_e64 v51, v0, v51
	v_mul_f32_e64 v48, v0, v48
	v_mul_f32_e64 v49, v0, v49
	v_mul_f32_e64 v46, v0, v46
	v_mul_f32_e64 v47, v0, v47
	v_pk_mul_f32 v[44:45], v[0:1], v[44:45] op_sel_hi:[0,1]
	v_pk_mul_f32 v[42:43], v[0:1], v[42:43] op_sel_hi:[0,1]
	v_pk_mul_f32 v[40:41], v[0:1], v[40:41] op_sel_hi:[0,1]
	v_pk_mul_f32 v[38:39], v[0:1], v[38:39] op_sel_hi:[0,1]
	s_waitcnt lgkmcnt(0)
	v_mfma_f32_32x32x16_bf16 v[4:19], v[104:107], v[132:135], v[4:19]
	v_mul_f32_e64 v36, v0, v36
	v_mul_f32_e64 v37, v0, v37
	v_mul_f32_e64 v34, v0, v34
	v_mul_f32_e64 v35, v0, v35
	v_mul_f32_e64 v32, v0, v32
	v_mul_f32_e64 v33, v0, v33
	v_pk_mul_f32 v[30:31], v[0:1], v[30:31] op_sel_hi:[0,1]
	v_pk_mul_f32 v[28:29], v[0:1], v[28:29] op_sel_hi:[0,1]
	v_pk_mul_f32 v[26:27], v[0:1], v[26:27] op_sel_hi:[0,1]
	v_pk_mul_f32 v[24:25], v[0:1], v[24:25] op_sel_hi:[0,1]
	v_pk_mul_f32 v[22:23], v[0:1], v[22:23] op_sel_hi:[0,1]
	v_pk_mul_f32 v[20:21], v[0:1], v[20:21] op_sel_hi:[0,1]
	v_pk_mul_f32 v[18:19], v[0:1], v[18:19] op_sel_hi:[0,1]
	v_pk_mul_f32 v[16:17], v[0:1], v[16:17] op_sel_hi:[0,1]
	v_pk_mul_f32 v[14:15], v[0:1], v[14:15] op_sel_hi:[0,1]
	v_pk_mul_f32 v[12:13], v[0:1], v[12:13] op_sel_hi:[0,1]
	v_pk_mul_f32 v[10:11], v[0:1], v[10:11] op_sel_hi:[0,1]
	v_pk_mul_f32 v[8:9], v[0:1], v[8:9] op_sel_hi:[0,1]
	v_pk_mul_f32 v[6:7], v[0:1], v[6:7] op_sel_hi:[0,1]
	v_pk_mul_f32 v[4:5], v[0:1], v[4:5] op_sel_hi:[0,1]
	v_mov_b32_e32 v0, v1
	v_mov_b64_e32 v[146:147], v[2:3]
	v_mov_b64_e32 v[142:143], v[2:3]
	v_mov_b64_e32 v[138:139], v[2:3]
	v_mov_b64_e32 v[134:135], v[2:3]
	v_mov_b64_e32 v[144:145], v[0:1]
	v_mov_b64_e32 v[140:141], v[0:1]
	v_mov_b64_e32 v[136:137], v[0:1]
	v_mov_b64_e32 v[132:133], v[0:1]
	v_mov_b32_e32 v104, v100
	v_mov_b32_e32 v105, v100
	v_mov_b32_e32 v106, v100
	v_mov_b32_e32 v107, v100
	v_mov_b32_e32 v110, v100
	v_mov_b32_e32 v111, v100
	v_mov_b32_e32 v112, v100
	v_mov_b32_e32 v113, v100
	v_mov_b32_e32 v114, v100
	v_mov_b32_e32 v115, v100
	s_branch .LBB0_1103
	.p2alignl 7, 3212836864
